# up-GEMM tile-index computation (S.next) moved into the MFMA shadow of the peeled first K-iteration
# speedup vs baseline: 1.0009x; 1.0009x over previous
; #define PG8_STAGE(bufoff, gbase, voff) do { _Pragma("unroll") for (int _i = 0; _i < 2; ++_i) \
;         __builtin_amdgcn_global_load_lds((const unsigned*)((const char*)(gbase) + (voff)[_i]), (PG8_LAS unsigned*)(lds + (bufoff) + ldsw + _i * 8192), 16, 0, 0); } while (0)
; #define PG8_LDA(dst, b, h) do { _Pragma("unroll") for (int m = 0; m < 4; ++m) _Pragma("unroll") for (int k = 0; k < 2; ++k) dst[m][k] = *(const PG8_LAS bf16x8*)(lds + PG8_SA(b, h) + aoff + m * 2048 + k * 1024); } while (0)
; #define PG8_LDB(dst, b, h) do { _Pragma("unroll") for (int n = 0; n < 2; ++n) _Pragma("unroll") for (int k = 0; k < 2; ++k) dst[n][k] = *(const PG8_LAS bf16x8*)(lds + PG8_SB(b, h) + boff + n * 2048 + k * 1024); } while (0)
; #define PG8_BAR __builtin_amdgcn_s_barrier()
;     __host__ __device__ bool next(int i, Unit& u) const {
;         const long L = (long)i * G + c; if (L >= nwg) return false;
;         int wgid = (int)L; { const int q = nwg / NXCD, r = nwg % NXCD, xcd = wgid % NXCD, off = wgid / NXCD; wgid = (xcd < r ? xcd * (q + 1) : r * (q + 1) + (xcd - r) * q) + off; }
;         const int nig = WGM * nN, gid = wgid / nig, fm = gid * WGM, gsz = (nM - fm) < WGM ? (nM - fm) : WGM;
;         u.pm = fm + ((wgid % nig) % gsz); u.pn = (wgid % nig) / gsz; return true;
;     }
; template <class Epi, class Sched, bool ALIGN_EPI = false, bool SP2 = false>
; __device__ __forceinline__ void gemm_phase(PG8_LAS unsigned char* lds, const Gemm g, const Sched& S, const Epi& E) {
;     ...
;         const bool has_next = S.next(ui + 1, nxt);
;         const char* nA = has_next ? (const char*)g.A + (size_t)nxt.pm * tstepA : cA; const char* nB = has_next ? (const char*)g.Bt + (size_t)nxt.pn * tstepB : cB;
;         for (int t = 0; t < nt; t += 2) {
;             const bool last = (t == nt - 2);
;             const char* a1 = cA + (size_t)(t + 1) * kstep;
;             const char* a2 = last ? nA : cA + (size_t)(t + 2) * kstep; const char* b2 = last ? nB : cB + (size_t)(t + 2) * kstep;
;             const char* a3 = a2 + kstep; const char* b3 = b2 + kstep;
;             if (last && has_next) S.a_ready(nxt);
;             if constexpr (SP2) {
;             PG8_LDB(B0, 0, 0); PG8_LDB(B1, 0, 1); PG8_SCHED; PG8_LDA(At, 0, 0); PG8_STAGE(PG8_SA(1, 1), a1 + hstepA, voffA);
;             PG8_WAIT_V(8); PG8_WAIT_L(0); PG8_BAR; PG8_MMA(0, 0, At, B0); PG8_MMA(0, 1, At, B1); PG8_BAR; PG8_SCHED;
.LBB0_441:
.LBB0_443:
	s_mov_b64 s[86:87], s[66:67]
	s_mov_b64 s[88:89], s[64:65]
	s_add_u32 s76, s64, 0x100
	s_addc_u32 s77, s65, 0
	s_add_u32 s64, s66, 0x40080
	s_addc_u32 s65, s67, 0
	s_mov_b32 s78, -2
	s_add_u32 s50, s64, 0xfffc0080
	s_addc_u32 s51, s65, -1
	s_add_i32 s79, 0, 0x10000
	s_cmp_eq_u32 s78, 12
	s_cselect_b32 s69, s21, s51
	s_cselect_b32 s68, s74, s50
	s_cselect_b32 s67, s15, s77
	s_cselect_b32 s66, s75, s76
	s_add_i32 s80, 0, 0x14000
	v_add_u32_e32 v156, s79, v143
	v_add_u32_e32 v160, s80, v143
	ds_read_b128 v[138:141], v156
	ds_read_b128 v[148:151], v156 offset:1024
	ds_read_b128 v[152:155], v156 offset:2048
	ds_read_b128 v[156:159], v156 offset:3072
	ds_read_b128 v[188:191], v160
	ds_read_b128 v[192:195], v160 offset:1024
	ds_read_b128 v[196:199], v160 offset:2048
	ds_read_b128 v[200:203], v160 offset:3072
	v_lshl_add_u64 v[160:161], s[64:65], 0, v[136:137]
	s_add_i32 m0, s19, 0xc000
	ds_read_b128 v[204:207], v147
	ds_read_b128 v[208:211], v147 offset:1024
	ds_read_b128 v[212:215], v147 offset:2048
	ds_read_b128 v[216:219], v147 offset:3072
	ds_read_b128 v[220:223], v147 offset:4096
	ds_read_b128 v[224:227], v147 offset:5120
	ds_read_b128 v[228:231], v147 offset:6144
	ds_read_b128 v[232:235], v147 offset:7168
	global_load_lds_dwordx4 v[160:161], off
	v_lshl_add_u64 v[160:161], s[64:65], 0, v[134:135]
	s_add_i32 m0, s19, 0xe000
	s_nop 0
	global_load_lds_dwordx4 v[160:161], off
	s_waitcnt vmcnt(8)
	s_waitcnt lgkmcnt(0)
	s_barrier
	s_setprio 1
	s_waitcnt lgkmcnt(0)
	v_mfma_f32_16x16x32_bf16 v[124:127], v[138:141], v[204:207], 0
	s_add_i32 s73, s73, 1
	s_mul_i32 s8, s73, s72
	s_mul_hi_u32 s9, s73, s37
	v_mfma_f32_16x16x32_bf16 v[116:119], v[152:155], v[204:207], 0
	s_add_i32 s9, s9, s8
	s_mul_i32 s8, s73, s37
	s_add_u32 s22, s8, s4
	v_mfma_f32_16x16x32_bf16 v[108:111], v[138:141], v[212:215], 0
	s_addc_u32 s23, s9, s17
	v_mov_b64_e32 v[0:1], s[34:35]
	v_cmp_lt_i64_e64 s[8:9], s[22:23], v[0:1]
	v_mfma_f32_16x16x32_bf16 v[100:103], v[152:155], v[212:215], 0
	s_ashr_i32 s14, s22, 31
	s_lshr_b32 s14, s14, 29
	s_add_i32 s14, s22, s14
	v_mfma_f32_16x16x32_bf16 v[92:95], v[138:141], v[220:223], 0
	s_ashr_i32 s15, s14, 3
	s_and_b32 s14, s14, -8
	s_sub_i32 s14, s22, s14
	v_mfma_f32_16x16x32_bf16 v[84:87], v[152:155], v[220:223], 0
	s_cmp_lt_i32 s14, 0
	s_cselect_b32 s20, s18, s16
	s_mul_i32 s14, s20, s14
	v_mfma_f32_16x16x32_bf16 v[76:79], v[138:141], v[228:231], 0
	s_add_i32 s14, s14, s15
	s_mul_hi_i32 s15, s14, 0x2e8ba2e9
	s_lshr_b32 s20, s15, 31
	v_mfma_f32_16x16x32_bf16 v[68:71], v[152:155], v[228:231], 0
	s_ashr_i32 s15, s15, 5
	s_add_i32 s15, s15, s20
	s_lshl_b32 s20, s15, 3
	v_mfma_f32_16x16x32_bf16 v[124:127], v[148:151], v[208:211], v[124:127]
	s_sub_i32 s21, s2, s20
	s_min_i32 s21, s21, 8
	s_abs_i32 s22, s21
	v_mfma_f32_16x16x32_bf16 v[116:119], v[156:159], v[208:211], v[116:119]
	v_cvt_f32_u32_e32 v0, s22
	s_sub_i32 s50, 0, s22
	s_mulk_i32 s15, 0xb0
	v_mfma_f32_16x16x32_bf16 v[108:111], v[148:151], v[216:219], v[108:111]
	s_sub_i32 s15, s14, s15
	v_rcp_iflag_f32_e32 v0, v0
	s_abs_i32 s14, s15
	v_mfma_f32_16x16x32_bf16 v[100:103], v[156:159], v[216:219], v[100:103]
	s_xor_b32 s23, s15, s21
	s_ashr_i32 s23, s23, 31
	v_mul_f32_e32 v0, 0x4f7ffffe, v0
	v_mfma_f32_16x16x32_bf16 v[92:95], v[148:151], v[224:227], v[92:95]
	v_cvt_u32_f32_e32 v0, v0
	s_nop 0
	v_readfirstlane_b32 s51, v0
	v_mfma_f32_16x16x32_bf16 v[84:87], v[156:159], v[224:227], v[84:87]
	s_mul_i32 s50, s50, s51
	s_mul_hi_u32 s50, s51, s50
	s_add_i32 s51, s51, s50
	v_mfma_f32_16x16x32_bf16 v[76:79], v[148:151], v[232:235], v[76:79]
	s_mul_hi_u32 s50, s14, s51
	s_mul_i32 s51, s50, s22
	s_sub_i32 s14, s14, s51
	v_mfma_f32_16x16x32_bf16 v[68:71], v[156:159], v[232:235], v[68:71]
	s_add_i32 s60, s50, 1
	s_sub_i32 s51, s14, s22
	s_cmp_ge_u32 s14, s22
	s_setprio 0
	s_setprio 1
	v_mfma_f32_16x16x32_bf16 v[120:123], v[188:191], v[204:207], 0
	s_cselect_b32 s50, s60, s50
	s_cselect_b32 s14, s51, s14
	s_add_i32 s51, s50, 1
	v_mfma_f32_16x16x32_bf16 v[112:115], v[196:199], v[204:207], 0
	s_cmp_ge_u32 s14, s22
	s_cselect_b32 s14, s51, s50
	s_xor_b32 s14, s14, s23
	v_mfma_f32_16x16x32_bf16 v[104:107], v[188:191], v[212:215], 0
	s_sub_i32 s14, s14, s23
	s_mul_i32 s21, s14, s21
	s_sub_i32 s15, s15, s21
	v_mfma_f32_16x16x32_bf16 v[96:99], v[196:199], v[212:215], 0
	s_add_i32 s20, s15, s20
	s_ashr_i32 s21, s20, 31
	s_lshl_b64 s[22:23], s[20:21], 19
	v_mfma_f32_16x16x32_bf16 v[88:91], v[188:191], v[220:223], 0
	s_add_u32 s22, s56, s22
	s_addc_u32 s23, s57, s23
	s_and_b64 s[50:51], s[8:9], exec
	v_mfma_f32_16x16x32_bf16 v[80:83], v[196:199], v[220:223], 0
	s_cselect_b32 s21, s23, s87
	s_cselect_b32 s74, s22, s86
	s_ashr_i32 s15, s14, 31
	v_mfma_f32_16x16x32_bf16 v[72:75], v[188:191], v[228:231], 0
	s_lshl_b64 s[50:51], s[14:15], 19
	s_add_u32 s60, s5, s50
	s_addc_u32 s61, s6, s51
	v_mfma_f32_16x16x32_bf16 v[64:67], v[196:199], v[228:231], 0
	s_and_b64 s[50:51], s[8:9], exec
	s_cselect_b32 s15, s61, s89
	s_cselect_b32 s75, s60, s88
	v_mfma_f32_16x16x32_bf16 v[120:123], v[192:195], v[208:211], v[120:123]
	v_mfma_f32_16x16x32_bf16 v[112:115], v[200:203], v[208:211], v[112:115]
	v_mfma_f32_16x16x32_bf16 v[104:107], v[192:195], v[216:219], v[104:107]
	v_mfma_f32_16x16x32_bf16 v[96:99], v[200:203], v[216:219], v[96:99]
	v_mfma_f32_16x16x32_bf16 v[88:91], v[192:195], v[224:227], v[88:91]
	v_mfma_f32_16x16x32_bf16 v[80:83], v[200:203], v[224:227], v[80:83]
	v_mfma_f32_16x16x32_bf16 v[72:75], v[192:195], v[232:235], v[72:75]
	v_mfma_f32_16x16x32_bf16 v[64:67], v[200:203], v[232:235], v[64:67]
	s_setprio 0
	s_barrier
; #define PG8_STAGE(bufoff, gbase, voff) do { _Pragma("unroll") for (int _i = 0; _i < 2; ++_i) \
;         __builtin_amdgcn_global_load_lds((const unsigned*)((const char*)(gbase) + (voff)[_i]), (PG8_LAS unsigned*)(lds + (bufoff) + ldsw + _i * 8192), 16, 0, 0); } while (0)
; #define PG8_LDA(dst, b, h) do { _Pragma("unroll") for (int m = 0; m < 4; ++m) _Pragma("unroll") for (int k = 0; k < 2; ++k) dst[m][k] = *(const PG8_LAS bf16x8*)(lds + PG8_SA(b, h) + aoff + m * 2048 + k * 1024); } while (0)
; #define PG8_LDB(dst, b, h) do { _Pragma("unroll") for (int n = 0; n < 2; ++n) _Pragma("unroll") for (int k = 0; k < 2; ++k) dst[n][k] = *(const PG8_LAS bf16x8*)(lds + PG8_SB(b, h) + boff + n * 2048 + k * 1024); } while (0)
; #define PG8_MMA(ai, bj, At, Bt) do { __builtin_amdgcn_s_setprio(1); _Pragma("unroll") for (int m = 0; m < 4; ++m) _Pragma("unroll") for (int n = 0; n < 2; ++n) _Pragma("unroll") for (int k = 0; k < 2; ++k) \
;         acc[ai][bj][m][n] = __builtin_amdgcn_mfma_f32_16x16x32_bf16(Bt[n][k], At[m][k], acc[ai][bj][m][n], 0, 0, 0); __builtin_amdgcn_s_setprio(0); } while (0)
; #define PG8_WAIT_V(n) asm volatile("s_waitcnt vmcnt(" #n ")" ::: "memory")
; #define PG8_WAIT_L(n) asm volatile("s_waitcnt lgkmcnt(" #n ")" ::: "memory")
; #define PG8_BAR __builtin_amdgcn_s_barrier()
; #define PG8_SCHED __builtin_amdgcn_sched_barrier(0)
; template <class Epi, class Sched, bool ALIGN_EPI = false, bool SP2 = false>
; __device__ __forceinline__ void gemm_phase(PG8_LAS unsigned char* lds, const Gemm g, const Sched& S, const Epi& E) {
;     ...
;             PG8_LDA(At, 0, 1); PG8_STAGE(PG8_SB(0, 0), b2, voffB); PG8_STAGE(PG8_SB(0, 1), b2 + hstepB, voffB); PG8_STAGE(PG8_SA(0, 0), a2, voffA);
;             PG8_WAIT_V(8); PG8_WAIT_L(0); PG8_BAR; PG8_MMA(1, 0, At, B0); PG8_MMA(1, 1, At, B1); PG8_BAR; PG8_SCHED;
;             PG8_LDB(B0, 1, 0); PG8_LDB(B1, 1, 1); PG8_SCHED; PG8_LDA(At, 1, 0); PG8_STAGE(PG8_SA(0, 1), a2 + hstepA, voffA);
;             PG8_WAIT_V(8); PG8_WAIT_L(0); PG8_BAR; PG8_MMA(0, 0, At, B0); PG8_MMA(0, 1, At, B1); PG8_BAR; PG8_SCHED;
	s_add_i32 s50, s79, s7
	v_lshl_add_u64 v[160:161], s[66:67], 0, v[144:145]
	s_mov_b32 m0, s50
	ds_read_b128 v[204:207], v147 offset:16384
	ds_read_b128 v[208:211], v147 offset:17408
	ds_read_b128 v[212:215], v147 offset:18432
	ds_read_b128 v[216:219], v147 offset:19456
	ds_read_b128 v[220:223], v147 offset:20480
	ds_read_b128 v[224:227], v147 offset:21504
	ds_read_b128 v[228:231], v147 offset:22528
	ds_read_b128 v[232:235], v147 offset:23552
	global_load_lds_dwordx4 v[160:161], off
	s_add_i32 m0, s50, 0x2000
	s_add_u32 s50, s66, 0x40000
	v_lshl_add_u64 v[174:175], s[66:67], 0, v[128:129]
	s_addc_u32 s51, s67, 0
	s_add_i32 s79, s80, s7
	global_load_lds_dwordx4 v[174:175], off
	v_lshl_add_u64 v[236:237], s[50:51], 0, v[144:145]
	s_mov_b32 m0, s79
	v_lshl_add_u64 v[238:239], s[68:69], 0, v[130:131]
	global_load_lds_dwordx4 v[236:237], off
	v_lshl_add_u64 v[236:237], s[50:51], 0, v[128:129]
	s_add_i32 m0, s79, 0x2000
	s_nop 0
	global_load_lds_dwordx4 v[236:237], off
	v_lshl_add_u64 v[236:237], s[68:69], 0, v[132:133]
	s_mov_b32 m0, s19
	s_nop 0
	global_load_lds_dwordx4 v[236:237], off
	s_mov_b32 m0, s24
	s_nop 0
	global_load_lds_dwordx4 v[238:239], off
	s_waitcnt vmcnt(8)
	s_waitcnt lgkmcnt(0)
	s_barrier
	s_setprio 1
	s_waitcnt lgkmcnt(0)
	v_mfma_f32_16x16x32_bf16 v[60:63], v[138:141], v[204:207], 0
	v_mfma_f32_16x16x32_bf16 v[52:55], v[152:155], v[204:207], 0
	v_mfma_f32_16x16x32_bf16 v[44:47], v[138:141], v[212:215], 0
	v_mfma_f32_16x16x32_bf16 v[36:39], v[152:155], v[212:215], 0
	v_mfma_f32_16x16x32_bf16 v[28:31], v[138:141], v[220:223], 0
	v_mfma_f32_16x16x32_bf16 v[20:23], v[152:155], v[220:223], 0
	v_mfma_f32_16x16x32_bf16 v[12:15], v[138:141], v[228:231], 0
	v_mfma_f32_16x16x32_bf16 v[4:7], v[152:155], v[228:231], 0
	v_mfma_f32_16x16x32_bf16 v[60:63], v[148:151], v[208:211], v[60:63]
	v_mfma_f32_16x16x32_bf16 v[52:55], v[156:159], v[208:211], v[52:55]
	v_mfma_f32_16x16x32_bf16 v[44:47], v[148:151], v[216:219], v[44:47]
	v_mfma_f32_16x16x32_bf16 v[36:39], v[156:159], v[216:219], v[36:39]
	v_mfma_f32_16x16x32_bf16 v[28:31], v[148:151], v[224:227], v[28:31]
	v_mfma_f32_16x16x32_bf16 v[20:23], v[156:159], v[224:227], v[20:23]
	v_mfma_f32_16x16x32_bf16 v[12:15], v[148:151], v[232:235], v[12:15]
	v_mfma_f32_16x16x32_bf16 v[4:7], v[156:159], v[232:235], v[4:7]
	s_setprio 0
	s_setprio 1
	v_mfma_f32_16x16x32_bf16 v[56:59], v[188:191], v[204:207], 0
	v_mfma_f32_16x16x32_bf16 v[48:51], v[196:199], v[204:207], 0
	v_mfma_f32_16x16x32_bf16 v[40:43], v[188:191], v[212:215], 0
	v_mfma_f32_16x16x32_bf16 v[32:35], v[196:199], v[212:215], 0
	v_mfma_f32_16x16x32_bf16 v[24:27], v[188:191], v[220:223], 0
	v_mfma_f32_16x16x32_bf16 v[16:19], v[196:199], v[220:223], 0
	v_mfma_f32_16x16x32_bf16 v[8:11], v[188:191], v[228:231], 0
	v_mfma_f32_16x16x32_bf16 v[0:3], v[196:199], v[228:231], 0
	v_mfma_f32_16x16x32_bf16 v[56:59], v[192:195], v[208:211], v[56:59]
	v_mfma_f32_16x16x32_bf16 v[48:51], v[200:203], v[208:211], v[48:51]
	v_mfma_f32_16x16x32_bf16 v[40:43], v[192:195], v[216:219], v[40:43]
	v_mfma_f32_16x16x32_bf16 v[32:35], v[200:203], v[216:219], v[32:35]
	v_mfma_f32_16x16x32_bf16 v[24:27], v[192:195], v[224:227], v[24:27]
	v_mfma_f32_16x16x32_bf16 v[16:19], v[200:203], v[224:227], v[16:19]
	v_mfma_f32_16x16x32_bf16 v[8:11], v[192:195], v[232:235], v[8:11]
	v_mfma_f32_16x16x32_bf16 v[0:3], v[200:203], v[232:235], v[0:3]
	s_setprio 0
	s_barrier
	s_add_i32 s79, 0, 0x18000
	s_add_i32 s80, 0, 0x1c000
	v_add_u32_e32 v156, s79, v143
	v_add_u32_e32 v162, s80, v143
	ds_read_b128 v[138:141], v156
	ds_read_b128 v[148:151], v156 offset:1024
	ds_read_b128 v[152:155], v156 offset:2048
	ds_read_b128 v[156:159], v156 offset:3072
	ds_read_b128 v[188:191], v162
	ds_read_b128 v[192:195], v162 offset:1024
	ds_read_b128 v[196:199], v162 offset:2048
	ds_read_b128 v[200:203], v162 offset:3072
	s_add_u32 s50, s68, 0x40000
	s_addc_u32 s51, s69, 0
	s_mov_b32 m0, s25
	v_lshl_add_u64 v[240:241], s[50:51], 0, v[132:133]
	ds_read_b128 v[204:207], v147 offset:32768
	ds_read_b128 v[208:211], v147 offset:33792
	ds_read_b128 v[212:215], v147 offset:34816
	ds_read_b128 v[216:219], v147 offset:35840
	ds_read_b128 v[220:223], v147 offset:36864
	ds_read_b128 v[224:227], v147 offset:37888
	ds_read_b128 v[228:231], v147 offset:38912
	ds_read_b128 v[232:235], v147 offset:39936
	global_load_lds_dwordx4 v[240:241], off
	v_lshl_add_u64 v[240:241], s[50:51], 0, v[130:131]
	s_mov_b32 m0, s31
	s_nop 0
	global_load_lds_dwordx4 v[240:241], off
	s_waitcnt vmcnt(8)
	s_waitcnt lgkmcnt(0)
	s_barrier
; #define PG8_STAGE(bufoff, gbase, voff) do { _Pragma("unroll") for (int _i = 0; _i < 2; ++_i) \
;         __builtin_amdgcn_global_load_lds((const unsigned*)((const char*)(gbase) + (voff)[_i]), (PG8_LAS unsigned*)(lds + (bufoff) + ldsw + _i * 8192), 16, 0, 0); } while (0)
; #define PG8_LDA(dst, b, h) do { _Pragma("unroll") for (int m = 0; m < 4; ++m) _Pragma("unroll") for (int k = 0; k < 2; ++k) dst[m][k] = *(const PG8_LAS bf16x8*)(lds + PG8_SA(b, h) + aoff + m * 2048 + k * 1024); } while (0)
; #define PG8_MMA(ai, bj, At, Bt) do { __builtin_amdgcn_s_setprio(1); _Pragma("unroll") for (int m = 0; m < 4; ++m) _Pragma("unroll") for (int n = 0; n < 2; ++n) _Pragma("unroll") for (int k = 0; k < 2; ++k) \
;         acc[ai][bj][m][n] = __builtin_amdgcn_mfma_f32_16x16x32_bf16(Bt[n][k], At[m][k], acc[ai][bj][m][n], 0, 0, 0); __builtin_amdgcn_s_setprio(0); } while (0)
; #define PG8_WAIT_V(n) asm volatile("s_waitcnt vmcnt(" #n ")" ::: "memory")
; #define PG8_WAIT_L(n) asm volatile("s_waitcnt lgkmcnt(" #n ")" ::: "memory")
; #define PG8_BAR __builtin_amdgcn_s_barrier()
; #define PG8_SCHED __builtin_amdgcn_sched_barrier(0)
; template <class Epi, class Sched, bool ALIGN_EPI = false, bool SP2 = false>
; __device__ __forceinline__ void gemm_phase(PG8_LAS unsigned char* lds, const Gemm g, const Sched& S, const Epi& E) {
;     ...
;             PG8_WAIT_V(8); PG8_WAIT_L(0); PG8_BAR; PG8_MMA(0, 0, At, B0); PG8_MMA(0, 1, At, B1); PG8_BAR; PG8_SCHED;
;             PG8_LDA(At, 1, 1); PG8_STAGE(PG8_SB(1, 0), b3, voffB); PG8_STAGE(PG8_SB(1, 1), b3 + hstepB, voffB); PG8_STAGE(PG8_SA(1, 0), a3, voffA);
;             PG8_WAIT_V(8); PG8_WAIT_L(0); PG8_BAR; PG8_MMA(1, 0, At, B0); PG8_MMA(1, 1, At, B1); PG8_BAR; PG8_SCHED;
	s_setprio 1
	s_waitcnt lgkmcnt(0)
	v_mfma_f32_16x16x32_bf16 v[124:127], v[138:141], v[204:207], v[124:127]
	v_mfma_f32_16x16x32_bf16 v[116:119], v[152:155], v[204:207], v[116:119]
	v_mfma_f32_16x16x32_bf16 v[108:111], v[138:141], v[212:215], v[108:111]
	v_mfma_f32_16x16x32_bf16 v[100:103], v[152:155], v[212:215], v[100:103]
	v_mfma_f32_16x16x32_bf16 v[92:95], v[138:141], v[220:223], v[92:95]
	v_mfma_f32_16x16x32_bf16 v[84:87], v[152:155], v[220:223], v[84:87]
	v_mfma_f32_16x16x32_bf16 v[76:79], v[138:141], v[228:231], v[76:79]
	v_mfma_f32_16x16x32_bf16 v[68:71], v[152:155], v[228:231], v[68:71]
	v_mfma_f32_16x16x32_bf16 v[124:127], v[148:151], v[208:211], v[124:127]
	v_mfma_f32_16x16x32_bf16 v[116:119], v[156:159], v[208:211], v[116:119]
	v_mfma_f32_16x16x32_bf16 v[108:111], v[148:151], v[216:219], v[108:111]
	v_mfma_f32_16x16x32_bf16 v[100:103], v[156:159], v[216:219], v[100:103]
	v_mfma_f32_16x16x32_bf16 v[92:95], v[148:151], v[224:227], v[92:95]
	v_mfma_f32_16x16x32_bf16 v[84:87], v[156:159], v[224:227], v[84:87]
	v_mfma_f32_16x16x32_bf16 v[76:79], v[148:151], v[232:235], v[76:79]
	v_mfma_f32_16x16x32_bf16 v[68:71], v[156:159], v[232:235], v[68:71]
	s_setprio 0
	s_setprio 1
	v_mfma_f32_16x16x32_bf16 v[120:123], v[188:191], v[204:207], v[120:123]
	v_mfma_f32_16x16x32_bf16 v[112:115], v[196:199], v[204:207], v[112:115]
	v_mfma_f32_16x16x32_bf16 v[104:107], v[188:191], v[212:215], v[104:107]
	v_mfma_f32_16x16x32_bf16 v[96:99], v[196:199], v[212:215], v[96:99]
	v_mfma_f32_16x16x32_bf16 v[88:91], v[188:191], v[220:223], v[88:91]
	v_mfma_f32_16x16x32_bf16 v[80:83], v[196:199], v[220:223], v[80:83]
	v_mfma_f32_16x16x32_bf16 v[72:75], v[188:191], v[228:231], v[72:75]
	v_mfma_f32_16x16x32_bf16 v[64:67], v[196:199], v[228:231], v[64:67]
	v_mfma_f32_16x16x32_bf16 v[120:123], v[192:195], v[208:211], v[120:123]
	v_mfma_f32_16x16x32_bf16 v[112:115], v[200:203], v[208:211], v[112:115]
	v_mfma_f32_16x16x32_bf16 v[104:107], v[192:195], v[216:219], v[104:107]
	v_mfma_f32_16x16x32_bf16 v[96:99], v[200:203], v[216:219], v[96:99]
	v_mfma_f32_16x16x32_bf16 v[88:91], v[192:195], v[224:227], v[88:91]
	v_mfma_f32_16x16x32_bf16 v[80:83], v[200:203], v[224:227], v[80:83]
	v_mfma_f32_16x16x32_bf16 v[72:75], v[192:195], v[232:235], v[72:75]
	v_mfma_f32_16x16x32_bf16 v[64:67], v[200:203], v[232:235], v[64:67]
	s_setprio 0
	s_barrier
	s_add_i32 s50, s79, s7
	v_lshl_add_u64 v[160:161], v[160:161], 0, s[48:49]
	s_mov_b32 m0, s50
	ds_read_b128 v[204:207], v147 offset:49152
	ds_read_b128 v[208:211], v147 offset:50176
	ds_read_b128 v[212:215], v147 offset:51200
	ds_read_b128 v[216:219], v147 offset:52224
	ds_read_b128 v[220:223], v147 offset:53248
	ds_read_b128 v[224:227], v147 offset:54272
	ds_read_b128 v[228:231], v147 offset:55296
	ds_read_b128 v[232:235], v147 offset:56320
	global_load_lds_dwordx4 v[160:161], off
	s_add_i32 m0, s50, 0x2000
	s_add_u32 s50, s66, 0x40080
	v_lshl_add_u64 v[160:161], v[174:175], 0, s[48:49]
	s_addc_u32 s51, s67, 0
	s_add_i32 s66, s80, s7
	global_load_lds_dwordx4 v[160:161], off
	v_lshl_add_u64 v[160:161], s[50:51], 0, v[144:145]
	s_mov_b32 m0, s66
	s_nop 0
	global_load_lds_dwordx4 v[160:161], off
	v_lshl_add_u64 v[160:161], s[50:51], 0, v[128:129]
	s_add_i32 m0, s66, 0x2000
	s_nop 0
	global_load_lds_dwordx4 v[160:161], off
	v_lshl_add_u64 v[160:161], v[236:237], 0, s[48:49]
	s_mov_b32 m0, s70
	s_nop 0
	global_load_lds_dwordx4 v[160:161], off
	v_lshl_add_u64 v[160:161], v[238:239], 0, s[48:49]
	s_mov_b32 m0, s71
	s_nop 0
	global_load_lds_dwordx4 v[160:161], off
	s_waitcnt vmcnt(8)
	s_waitcnt lgkmcnt(0)
	s_barrier
	s_setprio 1
	s_waitcnt lgkmcnt(0)
	v_mfma_f32_16x16x32_bf16 v[60:63], v[138:141], v[204:207], v[60:63]
	v_mfma_f32_16x16x32_bf16 v[52:55], v[152:155], v[204:207], v[52:55]
	v_mfma_f32_16x16x32_bf16 v[44:47], v[138:141], v[212:215], v[44:47]
	v_mfma_f32_16x16x32_bf16 v[36:39], v[152:155], v[212:215], v[36:39]
	v_mfma_f32_16x16x32_bf16 v[28:31], v[138:141], v[220:223], v[28:31]
	v_mfma_f32_16x16x32_bf16 v[20:23], v[152:155], v[220:223], v[20:23]
	v_mfma_f32_16x16x32_bf16 v[12:15], v[138:141], v[228:231], v[12:15]
	v_mfma_f32_16x16x32_bf16 v[4:7], v[152:155], v[228:231], v[4:7]
	v_mfma_f32_16x16x32_bf16 v[60:63], v[148:151], v[208:211], v[60:63]
	v_mfma_f32_16x16x32_bf16 v[52:55], v[156:159], v[208:211], v[52:55]
	v_mfma_f32_16x16x32_bf16 v[44:47], v[148:151], v[216:219], v[44:47]
	v_mfma_f32_16x16x32_bf16 v[36:39], v[156:159], v[216:219], v[36:39]
	v_mfma_f32_16x16x32_bf16 v[28:31], v[148:151], v[224:227], v[28:31]
	v_mfma_f32_16x16x32_bf16 v[20:23], v[156:159], v[224:227], v[20:23]
	v_mfma_f32_16x16x32_bf16 v[12:15], v[148:151], v[232:235], v[12:15]
	v_mfma_f32_16x16x32_bf16 v[4:7], v[156:159], v[232:235], v[4:7]
	s_setprio 0
	s_setprio 1
	v_mfma_f32_16x16x32_bf16 v[56:59], v[188:191], v[204:207], v[56:59]
	v_mfma_f32_16x16x32_bf16 v[48:51], v[196:199], v[204:207], v[48:51]
	v_mfma_f32_16x16x32_bf16 v[40:43], v[188:191], v[212:215], v[40:43]
	v_mfma_f32_16x16x32_bf16 v[32:35], v[196:199], v[212:215], v[32:35]
	v_mfma_f32_16x16x32_bf16 v[24:27], v[188:191], v[220:223], v[24:27]
	v_mfma_f32_16x16x32_bf16 v[16:19], v[196:199], v[220:223], v[16:19]
	v_mfma_f32_16x16x32_bf16 v[8:11], v[188:191], v[228:231], v[8:11]
	v_mfma_f32_16x16x32_bf16 v[0:3], v[196:199], v[228:231], v[0:3]
	v_mfma_f32_16x16x32_bf16 v[56:59], v[192:195], v[208:211], v[56:59]
	v_mfma_f32_16x16x32_bf16 v[48:51], v[200:203], v[208:211], v[48:51]
	v_mfma_f32_16x16x32_bf16 v[40:43], v[192:195], v[216:219], v[40:43]
	v_mfma_f32_16x16x32_bf16 v[32:35], v[200:203], v[216:219], v[32:35]
	v_mfma_f32_16x16x32_bf16 v[24:27], v[192:195], v[224:227], v[24:27]
	v_mfma_f32_16x16x32_bf16 v[16:19], v[200:203], v[224:227], v[16:19]
	v_mfma_f32_16x16x32_bf16 v[8:11], v[192:195], v[232:235], v[8:11]
	v_mfma_f32_16x16x32_bf16 v[0:3], v[200:203], v[232:235], v[0:3]
	s_setprio 0
	s_barrier
	s_add_i32 s78, s78, 2
	s_add_u32 s76, s76, 0x100
	s_addc_u32 s77, s77, 0
	s_add_u32 s64, s64, 0x100
	s_addc_u32 s65, s65, 0
